# hand-written final stages for retention and hgrn units (batched LDS fragments); L2 prefetch loads now return into a dead register
# baseline (speedup 1.0000x reference)
; __device__ __forceinline__ void mixer_local_phase(const Ctx& X, LAS unsigned char* lds, int layer, int tid, int wave, int lane) {
;     ...
;     for (int it_ = 0; it_ < nit_; ++it_) {
;         const int u = (int)blockIdx.x + (int)gridDim.x * ((it_ + (int)(blockIdx.x >> 3)) % nit_);
;         if (u >= 3584) continue;
;         asm volatile("" : "+v"(tid_h), "+v"(lane), "+v"(tid));
;         if (u < 3072) { const int mixer = u >> 10, idx = u & 1023, hp = idx & 1, cb = idx >> 1, b = cb >> 7, c = cb & 127, h = hp * 2 + hs;
;             if (mixer == 0) { ret_unit(X, hl, b, c, h, tid_h, w4, lane);
;             } else if (mixer == 1) { gdn_unit(X, hl, b, c, h, tid_h, w4, lane, layer);
;             } else { hgrn_unit(X, hl, b, c, h, tid_h, w4, lane, layer);
;             }
;         } else { const int cb = u - 3072; conf_unit(X, lds, cb >> 7, cb & 127, tid, wave, lane, layer);
.LpfC_go:
	s_lshr_b32 s100, s98, 7
	s_lshl_b32 s100, s100, 13
	s_and_b32 s98, s98, 0x7f
	s_lshl_b32 s98, s98, 6
	s_add_u32 s98, s98, s100
	s_mov_b32 s32, s98
	s_mul_i32 s98, s98, 0x1c00
	s_add_u32 s98, s98, s99
	s_add_u32 s82, s76, s98
	s_addc_u32 s83, s77, 0
	v_mad_u32_u24 v237, v237, s71, v238
	global_load_dword v234, v237, s[82:83]
	v_readfirstlane_b32 s100, v224
	s_cmp_eq_u32 s101, 1
	s_cbranch_scc1 .LpfC_chalo
	s_cmpk_ge_u32 s100, 64
	s_cbranch_scc1 .LpfC_gba
	s_sub_u32 s82, s82, 0x5400
	s_subb_u32 s83, s83, 0
	v_lshrrev_b32_e32 v239, 3, v224
	v_min_u32_e32 v239, 2, v239
	v_mad_u32_u24 v239, v239, s71, v238
	global_load_dword v234, v239, s[82:83]
	s_branch .LpfC_done
.LpfC_gba:
	s_cmpk_ge_u32 s100, 128
	s_cbranch_scc1 .LpfC_done
	s_lshl_b32 s32, s32, 5
	s_add_u32 s32, s32, 0x1f740000
	s_add_u32 s82, s30, s32
	s_addc_u32 s83, s31, 0
	v_and_b32_e32 v239, 63, v224
	v_min_u32_e32 v239, 15, v239
	v_lshlrev_b32_e32 v239, 7, v239
	global_load_dword v234, v239, s[82:83]
	s_branch .LpfC_done
.LpfC_chalo:
	s_cmpk_ge_u32 s100, 256
	s_cbranch_scc1 .LpfC_done
	s_sub_u32 s82, s82, 0x38000
	s_subb_u32 s83, s83, 0
	global_load_dword v234, v237, s[82:83]

; __device__ __forceinline__ bf16_t f2bf(float f) { return (bf16_t)(pk2(f, 0.f) & 0xffffu); }
; __device__ __forceinline__ float fexp(float x) { return __expf(x); }
; #define LBAR() do { asm volatile("s_waitcnt lgkmcnt(0)" ::: "memory"); __builtin_amdgcn_s_barrier(); asm volatile("" ::: "memory"); } while (0)
; __device__ __forceinline__ void hgrn_unit(const Ctx& X, LAS unsigned char* hl, int b, int c, int h, int tid_h, int w4, int lane, int layer) {
;     ...
; #pragma unroll
;         for (int ct = 0; ct < 4; ++ct)
; #pragma unroll
;             for (int j = 0; j < 4; ++j) { const int ii = 16 * I + 4 * q + j, col = 16 * ct + r;
;                 QT[ii * LT + col] = f2bf((ct <= I && ii >= col) ? acc[ct][j] : 0.f); }
;     }
;     LBAR();
;     {
; #pragma unroll
;         for (int e = 0; e < 16; ++e) { VT[(ds + e) * LT + i] = f2bf(vv[e]); KDT[(ds + e) * LT + i] = f2bf(kk[e] * fexp(G63[e] - Gi[e])); }
;     }
.LBB0_317:
	v_ashrrev_i32_e32 v96, 4, v130
	v_lshl_add_u32 v98, v96, 2, s39
	v_cmp_ge_i32_e32 vcc, v98, v91
	v_lshlrev_b32_e32 v99, 1, v91
	v_mul_lo_u32 v100, v98, s44
	v_cndmask_b32_e32 v18, 0, v18, vcc
	s_waitcnt lgkmcnt(0)
	v_cvt_pk_bf16_f32 v18, v18, v157
	v_add3_u32 v74, v74, v99, v100
	ds_write_b16 v74, v18
	v_or_b32_e32 v18, 1, v98
	v_cmp_ge_i32_e32 vcc, v18, v91
	v_or_b32_e32 v99, 16, v91
	v_readlane_b32 s6, v252, 48
	v_cndmask_b32_e32 v19, 0, v19, vcc
	v_cvt_pk_bf16_f32 v19, v19, v157
	ds_write_b16 v74, v19 offset:144
	v_or_b32_e32 v19, 2, v98
	v_cmp_ge_i32_e32 vcc, v19, v91
	v_readlane_b32 s7, v252, 49
	v_or_b32_e32 v22, 48, v91
	v_cndmask_b32_e32 v20, 0, v20, vcc
	v_cvt_pk_bf16_f32 v20, v20, v157
	ds_write_b16 v74, v20 offset:288
	v_or_b32_e32 v20, 3, v98
	v_cmp_ge_i32_e32 vcc, v20, v91
	v_and_b32_e32 v97, 0xffff0000, v6
	v_lshlrev_b32_e32 v6, 16, v6
	v_cndmask_b32_e32 v21, 0, v21, vcc
	v_cmp_lt_i32_e32 vcc, v98, v99
	s_or_b64 s[4:5], s[40:41], vcc
	v_cndmask_b32_e64 v14, v14, 0, s[4:5]
	v_cmp_lt_i32_e32 vcc, v18, v99
	v_cvt_pk_bf16_f32 v21, v21, v157
	ds_write_b16 v74, v21 offset:432
	v_cvt_pk_bf16_f32 v14, v14, v157
	s_or_b64 s[4:5], s[40:41], vcc
	ds_write_b16 v74, v14 offset:32
	v_cndmask_b32_e64 v14, v15, 0, s[4:5]
	v_cmp_lt_i32_e32 vcc, v19, v99
	v_cvt_pk_bf16_f32 v14, v14, v157
	s_or_b64 s[4:5], s[40:41], vcc
	ds_write_b16 v74, v14 offset:176
	v_cndmask_b32_e64 v14, v16, 0, s[4:5]
	v_cmp_lt_i32_e32 vcc, v20, v99
	v_cvt_pk_bf16_f32 v14, v14, v157
	s_or_b64 s[4:5], s[40:41], vcc
	ds_write_b16 v74, v14 offset:320
	v_cndmask_b32_e64 v14, v17, 0, s[4:5]
	v_cvt_pk_bf16_f32 v14, v14, v157
	ds_write_b16 v74, v14 offset:464
	v_or_b32_e32 v14, 32, v91
	v_cmp_lt_i32_e32 vcc, v98, v14
	s_or_b64 s[4:5], s[6:7], vcc
	v_cndmask_b32_e64 v15, v30, 0, s[4:5]
	v_cmp_lt_i32_e32 vcc, v18, v14
	v_cvt_pk_bf16_f32 v15, v15, v157
	s_or_b64 s[4:5], s[6:7], vcc
	ds_write_b16 v74, v15 offset:64
	v_cndmask_b32_e64 v15, v31, 0, s[4:5]
	v_cmp_lt_i32_e32 vcc, v19, v14
	v_cvt_pk_bf16_f32 v15, v15, v157
	s_or_b64 s[4:5], s[6:7], vcc
	v_cmp_lt_i32_e32 vcc, v20, v14
	ds_write_b16 v74, v15 offset:208
	v_cndmask_b32_e64 v15, v32, 0, s[4:5]
	s_or_b64 s[4:5], s[6:7], vcc
	v_readlane_b32 s6, v252, 52
	v_cndmask_b32_e64 v14, v33, 0, s[4:5]
	v_cmp_lt_i32_e32 vcc, v98, v22
	v_readlane_b32 s7, v252, 53
	v_cvt_pk_bf16_f32 v15, v15, v157
	ds_write_b16 v74, v15 offset:352
	v_cvt_pk_bf16_f32 v14, v14, v157
	s_or_b64 s[4:5], s[6:7], vcc
	ds_write_b16 v74, v14 offset:496
	v_cndmask_b32_e64 v14, v34, 0, s[4:5]
	v_cmp_lt_i32_e32 vcc, v18, v22
	v_cvt_pk_bf16_f32 v14, v14, v157
	s_or_b64 s[4:5], s[6:7], vcc
	ds_write_b16 v74, v14 offset:96
	v_cndmask_b32_e64 v14, v35, 0, s[4:5]
	v_cmp_lt_i32_e32 vcc, v19, v22
	v_cvt_pk_bf16_f32 v14, v14, v157
	s_or_b64 s[4:5], s[6:7], vcc
	ds_write_b16 v74, v14 offset:240
	v_cndmask_b32_e64 v14, v36, 0, s[4:5]
	v_cmp_lt_i32_e32 vcc, v20, v22
	v_cvt_pk_bf16_f32 v14, v14, v157
	s_or_b64 s[4:5], s[6:7], vcc
	v_sub_f32_e32 v15, v40, v38
	ds_write_b16 v74, v14 offset:384
	v_cndmask_b32_e64 v14, v37, 0, s[4:5]
	v_mul_f32_e32 v15, 0x3fb8aa3b, v15
	v_cvt_pk_bf16_f32 v14, v14, v157
	v_exp_f32_e32 v15, v15
	ds_write_b16 v74, v14 offset:528
	v_mul_u32_u24_e32 v14, 0x48, v73
	v_add_lshl_u32 v14, v14, v72, 1
	s_waitcnt lgkmcnt(0)
	s_barrier
	v_cvt_pk_bf16_f32 v6, v6, v157
	v_add_u32_e32 v16, v71, v14
	ds_write_b16 v16, v6
	v_mul_f32_e32 v6, v90, v15
	v_sub_f32_e32 v15, v41, v39
	v_mul_f32_e32 v15, 0x3fb8aa3b, v15
	v_exp_f32_e32 v15, v15
	v_cvt_pk_bf16_f32 v6, v6, v157
	v_add_u32_e32 v14, v70, v14
	ds_write_b16 v14, v6
	v_cvt_pk_bf16_f32 v6, v97, v157
	ds_write_b16 v16, v6 offset:144
	v_mul_f32_e32 v6, v89, v15
	v_sub_f32_e32 v15, v44, v42
	v_mul_f32_e32 v15, 0x3fb8aa3b, v15
	v_and_b32_e32 v29, 0xffff0000, v7
	v_lshlrev_b32_e32 v7, 16, v7
	v_cvt_pk_bf16_f32 v6, v6, v157
	v_exp_f32_e32 v15, v15
	ds_write_b16 v14, v6 offset:144
	v_cvt_pk_bf16_f32 v6, v7, v157
	v_sub_f32_e32 v7, v45, v43
	v_mul_f32_e32 v7, 0x3fb8aa3b, v7
	v_exp_f32_e32 v7, v7
	ds_write_b16 v16, v6 offset:288
	v_mul_f32_e32 v6, v88, v15
	v_cvt_pk_bf16_f32 v6, v6, v157
	ds_write_b16 v14, v6 offset:288
	v_cvt_pk_bf16_f32 v6, v29, v157
	ds_write_b16 v16, v6 offset:432
	v_mul_f32_e32 v6, v87, v7
	v_sub_f32_e32 v7, v48, v46
	v_mul_f32_e32 v7, 0x3fb8aa3b, v7
	v_exp_f32_e32 v7, v7
	v_cvt_pk_bf16_f32 v6, v6, v157
	v_and_b32_e32 v28, 0xffff0000, v8
	v_lshlrev_b32_e32 v8, 16, v8
	ds_write_b16 v14, v6 offset:432
	v_cvt_pk_bf16_f32 v6, v8, v157
	ds_write_b16 v16, v6 offset:576
	v_mul_f32_e32 v6, v86, v7
	v_sub_f32_e32 v7, v49, v47
	v_mul_f32_e32 v7, 0x3fb8aa3b, v7
	v_exp_f32_e32 v7, v7
	v_cvt_pk_bf16_f32 v6, v6, v157
	ds_write_b16 v14, v6 offset:576
	v_cvt_pk_bf16_f32 v6, v28, v157
	ds_write_b16 v16, v6 offset:720
	v_mul_f32_e32 v6, v85, v7
	v_sub_f32_e32 v7, v52, v50
	v_mul_f32_e32 v7, 0x3fb8aa3b, v7
	v_exp_f32_e32 v7, v7
	v_cvt_pk_bf16_f32 v6, v6, v157
	v_and_b32_e32 v27, 0xffff0000, v9
	v_lshlrev_b32_e32 v9, 16, v9
	ds_write_b16 v14, v6 offset:720
	v_cvt_pk_bf16_f32 v6, v9, v157
	ds_write_b16 v16, v6 offset:864
	v_mul_f32_e32 v6, v84, v7
	v_sub_f32_e32 v7, v53, v51
	v_mul_f32_e32 v7, 0x3fb8aa3b, v7
	v_exp_f32_e32 v7, v7
	v_cvt_pk_bf16_f32 v6, v6, v157
	ds_write_b16 v14, v6 offset:864
	v_cvt_pk_bf16_f32 v6, v27, v157
	ds_write_b16 v16, v6 offset:1008
	v_mul_f32_e32 v6, v83, v7
	v_sub_f32_e32 v7, v56, v54
	v_mul_f32_e32 v7, 0x3fb8aa3b, v7
	v_exp_f32_e32 v7, v7
	v_cvt_pk_bf16_f32 v6, v6, v157
	s_waitcnt vmcnt(2)
; __device__ __forceinline__ bf16_t f2bf(float f) { return (bf16_t)(pk2(f, 0.f) & 0xffffu); }
; __device__ __forceinline__ float fexp(float x) { return __expf(x); }
; #define LBAR() do { asm volatile("s_waitcnt lgkmcnt(0)" ::: "memory"); __builtin_amdgcn_s_barrier(); asm volatile("" ::: "memory"); } while (0)
; __device__ __forceinline__ void hgrn_unit(const Ctx& X, LAS unsigned char* hl, int b, int c, int h, int tid_h, int w4, int lane, int layer) {
;     ...
;         for (int e = 0; e < 16; ++e) { VT[(ds + e) * LT + i] = f2bf(vv[e]); KDT[(ds + e) * LT + i] = f2bf(kk[e] * fexp(G63[e] - Gi[e])); }
;     }
;     LBAR();
; #pragma unroll
;     for (int ct = 0; ct < 4; ++ct) acc[ct] = mma16(QT, 16 * w4, VT, 16 * ct, (f32x4){0.f, 0.f, 0.f, 0.f}, r, q);
;     store_oloc(WSP(bf16_t, WS_OLOC), uid, w4, lane, acc);
; #pragma unroll
;     for (int ct = 0; ct < 4; ++ct) acc[ct] = mma16(KDT, 16 * w4, VT, 16 * ct, (f32x4){0.f, 0.f, 0.f, 0.f}, r, q);
;     store_bc(WSP(bf16_t, WS_BCS), uid, w4, r, q, acc);
;     LBAR();
	v_and_b32_e32 v26, 0xffff0000, v10
	v_lshlrev_b32_e32 v10, 16, v10
	ds_write_b16 v14, v6 offset:1008
	v_cvt_pk_bf16_f32 v6, v10, v157
	ds_write_b16 v16, v6 offset:1152
	v_mul_f32_e32 v6, v82, v7
	v_sub_f32_e32 v7, v57, v55
	v_mul_f32_e32 v7, 0x3fb8aa3b, v7
	v_exp_f32_e32 v7, v7
	v_cvt_pk_bf16_f32 v6, v6, v157
	ds_write_b16 v14, v6 offset:1152
	v_cvt_pk_bf16_f32 v6, v26, v157
	ds_write_b16 v16, v6 offset:1296
	v_mul_f32_e32 v6, v81, v7
	v_sub_f32_e32 v7, v60, v58
	v_mul_f32_e32 v7, 0x3fb8aa3b, v7
	v_exp_f32_e32 v7, v7
	v_cvt_pk_bf16_f32 v6, v6, v157
	v_and_b32_e32 v25, 0xffff0000, v11
	v_lshlrev_b32_e32 v11, 16, v11
	ds_write_b16 v14, v6 offset:1296
	v_cvt_pk_bf16_f32 v6, v11, v157
	ds_write_b16 v16, v6 offset:1440
	v_mul_f32_e32 v6, v80, v7
	v_sub_f32_e32 v7, v61, v59
	v_mul_f32_e32 v7, 0x3fb8aa3b, v7
	v_exp_f32_e32 v7, v7
	v_cvt_pk_bf16_f32 v6, v6, v157
	ds_write_b16 v14, v6 offset:1440
	v_cvt_pk_bf16_f32 v6, v25, v157
	ds_write_b16 v16, v6 offset:1584
	v_mul_f32_e32 v6, v79, v7
	v_sub_f32_e32 v7, v64, v62
	v_mul_f32_e32 v7, 0x3fb8aa3b, v7
	v_exp_f32_e32 v7, v7
	v_cvt_pk_bf16_f32 v6, v6, v157
	v_and_b32_e32 v24, 0xffff0000, v12
	v_lshlrev_b32_e32 v12, 16, v12
	ds_write_b16 v14, v6 offset:1584
	v_cvt_pk_bf16_f32 v6, v12, v157
	ds_write_b16 v16, v6 offset:1728
	v_mul_f32_e32 v6, v78, v7
	v_sub_f32_e32 v7, v65, v63
	v_mul_f32_e32 v7, 0x3fb8aa3b, v7
	v_exp_f32_e32 v7, v7
	v_cvt_pk_bf16_f32 v6, v6, v157
	ds_write_b16 v14, v6 offset:1728
	v_cvt_pk_bf16_f32 v6, v24, v157
	ds_write_b16 v16, v6 offset:1872
	v_mul_f32_e32 v6, v77, v7
	v_sub_f32_e32 v7, v68, v66
	v_mul_f32_e32 v7, 0x3fb8aa3b, v7
	v_exp_f32_e32 v7, v7
	v_cvt_pk_bf16_f32 v6, v6, v157
	v_and_b32_e32 v23, 0xffff0000, v13
	v_lshlrev_b32_e32 v13, 16, v13
	ds_write_b16 v14, v6 offset:1872
	v_cvt_pk_bf16_f32 v6, v13, v157
	ds_write_b16 v16, v6 offset:2016
	v_mul_f32_e32 v6, v76, v7
	v_sub_f32_e32 v7, v69, v67
	v_mul_f32_e32 v7, 0x3fb8aa3b, v7
	v_exp_f32_e32 v7, v7
	v_cvt_pk_bf16_f32 v6, v6, v157
	ds_write_b16 v14, v6 offset:2016
	v_cvt_pk_bf16_f32 v6, v23, v157
	ds_write_b16 v16, v6 offset:2160
	v_mul_f32_e32 v6, v75, v7
	v_cvt_pk_bf16_f32 v6, v6, v157
	ds_write_b16 v14, v6 offset:2160
	s_waitcnt lgkmcnt(0)
	s_barrier
	v_add_u32_e32 v22, v71, v92
	v_add_u32_e32 v44, v22, v95
	v_mad_u32_u24 v34, v99, s44, v22
	v_mul_u32_u24_e32 v26, 0x90, v93
	v_add3_u32 v18, v70, v26, v92
	ds_read_b128 v[46:49], v94
	ds_read_b128 v[50:53], v94 offset:64
	ds_read_b128 v[54:57], v44
	ds_read_b128 v[58:61], v44 offset:64
	ds_read_b128 v[62:65], v34
	ds_read_b128 v[66:69], v34 offset:64
	ds_read_b128 v[72:75], v34 offset:2304
	ds_read_b128 v[76:79], v34 offset:2368
	ds_read_b128 v[80:83], v44 offset:6912
	ds_read_b128 v[102:105], v44 offset:6976
	ds_read_b128 v[134:137], v18
	ds_read_b128 v[138:141], v18 offset:64
	s_add_u32 s4, s79, s0
	s_addc_u32 s5, s80, s1
	s_add_u32 s0, s74, s0
	s_addc_u32 s1, s75, s1
	v_lshlrev_b32_e32 v42, 4, v130
	v_ashrrev_i32_e32 v43, 31, v42
	v_lshl_add_u64 v[38:39], v[42:43], 1, s[4:5]
	v_lshl_or_b32 v12, v91, 2, s81
	v_lshl_add_u32 v12, v96, 6, v12
	v_ashrrev_i32_e32 v13, 31, v12
	v_lshl_add_u64 v[14:15], v[12:13], 1, s[0:1]
	v_add_u32_e32 v16, 0x800, v12
	v_ashrrev_i32_e32 v17, 31, v16
	v_lshl_add_u64 v[16:17], v[16:17], 1, s[0:1]
	v_add_u32_e32 v20, 0xc00, v12
	v_ashrrev_i32_e32 v21, 31, v20
	v_lshl_add_u64 v[20:21], v[20:21], 1, s[0:1]
	s_waitcnt lgkmcnt(2)
	v_mfma_f32_16x16x32_bf16 v[186:189], v[46:49], v[54:57], 0
	v_mfma_f32_16x16x32_bf16 v[190:193], v[46:49], v[62:65], 0
	v_mfma_f32_16x16x32_bf16 v[194:197], v[46:49], v[72:75], 0
	v_mfma_f32_16x16x32_bf16 v[198:201], v[46:49], v[80:83], 0
	v_mfma_f32_16x16x32_bf16 v[186:189], v[50:53], v[58:61], v[186:189]
	v_mfma_f32_16x16x32_bf16 v[190:193], v[50:53], v[66:69], v[190:193]
	v_mfma_f32_16x16x32_bf16 v[194:197], v[50:53], v[76:79], v[194:197]
	v_mfma_f32_16x16x32_bf16 v[198:201], v[50:53], v[102:105], v[198:201]
	s_waitcnt lgkmcnt(0)
	v_mfma_f32_16x16x32_bf16 v[202:205], v[134:137], v[54:57], 0
	v_mfma_f32_16x16x32_bf16 v[206:209], v[134:137], v[62:65], 0
	v_mfma_f32_16x16x32_bf16 v[210:213], v[134:137], v[72:75], 0
	v_mfma_f32_16x16x32_bf16 v[214:217], v[134:137], v[80:83], 0
	v_mfma_f32_16x16x32_bf16 v[202:205], v[138:141], v[58:61], v[202:205]
	v_mfma_f32_16x16x32_bf16 v[206:209], v[138:141], v[66:69], v[206:209]
	v_mfma_f32_16x16x32_bf16 v[210:213], v[138:141], v[76:79], v[210:213]
	v_mfma_f32_16x16x32_bf16 v[214:217], v[138:141], v[102:105], v[214:217]
	v_cvt_pk_bf16_f32 v218, v186, v187
	v_cvt_pk_bf16_f32 v219, v188, v189
	v_cvt_pk_bf16_f32 v220, v190, v191
	v_cvt_pk_bf16_f32 v221, v192, v193
	v_cvt_pk_bf16_f32 v236, v194, v195
	v_cvt_pk_bf16_f32 v237, v196, v197
	v_cvt_pk_bf16_f32 v238, v198, v199
	v_cvt_pk_bf16_f32 v239, v200, v201
	global_store_dwordx4 v[38:39], v[218:221], off nt
	global_store_dwordx4 v[38:39], v[236:239], off offset:16 nt
	v_cvt_pk_bf16_f32 v246, v202, v203
	v_cvt_pk_bf16_f32 v247, v204, v205
	v_cvt_pk_bf16_f32 v248, v206, v207
	v_cvt_pk_bf16_f32 v249, v208, v209
	v_cvt_pk_bf16_f32 v250, v210, v211
	v_cvt_pk_bf16_f32 v251, v212, v213
	v_cvt_pk_bf16_f32 v226, v214, v215
	v_cvt_pk_bf16_f32 v227, v216, v217
	global_store_dwordx2 v[14:15], v[246:247], off
	global_store_dwordx2 v[14:15], v[248:249], off offset:2048
	global_store_dwordx2 v[16:17], v[250:251], off
	global_store_dwordx2 v[20:21], v[226:227], off
	s_waitcnt lgkmcnt(0)
	s_barrier
	s_mov_b64 s[0:1], 0

; __device__ __forceinline__ float bf2f(bf16_t b) { return __uint_as_float((unsigned)b << 16); }
; __device__ __forceinline__ bf16_t f2bf(float f) { return (bf16_t)(pk2(f, 0.f) & 0xffffu); }
; __device__ __forceinline__ float fexp(float x) { return __expf(x); }
; __device__ __forceinline__ void gdn_unit(const Ctx& X, LAS unsigned char* hl, int b, int c, int h, int tid_h, int w4, int lane, int layer) {
;     ...
;     {
;         f32x4 acc[4];
;         const float eG63 = fexp(Gs[63]);
; #pragma unroll
;         for (int ct = 0; ct < 4; ++ct) acc[ct] = mma16(P, 16 * w4, WT, 16 * ct, (f32x4){0.f, 0.f, 0.f, 0.f}, r, q);
;         bf16_t* qe = WSP(bf16_t, WS_QEFF) + (size_t)uid * 4096;
; #pragma unroll
;         for (int ct = 0; ct < 4; ++ct)
; #pragma unroll
;             for (int j = 0; j < 4; ++j) { const int ii = 16 * w4 + 4 * q + j, col = 16 * ct + r;
;                 qe[ii * 64 + col] = f2bf(bf2f(Q[ii * LT + col]) * fexp(Gs[ii]) - acc[ct][j]); }
; #pragma unroll
;         for (int ct = 0; ct < 4; ++ct) acc[ct] = mma16(P, 16 * w4, UT, 16 * ct, (f32x4){0.f, 0.f, 0.f, 0.f}, r, q);
;         store_oloc(WSP(bf16_t, WS_OLOC), uid, w4, lane, acc);
; #pragma unroll
;         for (int ct = 0; ct < 4; ++ct) acc[ct] = mma16(KDT, 16 * w4, WT, 16 * ct, (f32x4){0.f, 0.f, 0.f, 0.f}, r, q);
;         bf16_t* mm = WSP(bf16_t, WS_MM) + (size_t)(uid - 2048) * 4096;
; #pragma unroll
;         for (int ct = 0; ct < 4; ++ct)
; #pragma unroll
;             for (int j = 0; j < 4; ++j) { const int ii = 16 * w4 + 4 * q + j, col = 16 * ct + r;
;                 mm[((w4 * 2 + (ct >> 1)) * 64 + (r >> 2) * 16 + 4 * q + j) * 8 + (ct & 1) * 4 + (r & 3)] = f2bf((ii == col ? eG63 : 0.f) - acc[ct][j]); }
; #pragma unroll
;         for (int ct = 0; ct < 4; ++ct) acc[ct] = mma16(KDT, 16 * w4, UT, 16 * ct, (f32x4){0.f, 0.f, 0.f, 0.f}, r, q);
;         store_bc(WSP(bf16_t, WS_BCS), uid, w4, r, q, acc);
;     }
.LBB0_619:
	s_waitcnt lgkmcnt(0)
	s_barrier
	v_bfe_u32 v54, v224, 6, 2
	v_and_b32_e32 v55, 15, v232
	v_lshrrev_b32_e32 v56, 4, v232
	v_lshl_or_b32 v57, v54, 4, v55
	v_mul_u32_u24_e32 v58, 0x90, v57
	v_mul_u32_u24_e32 v59, 0x90, v55
	v_lshl_add_u32 v60, v56, 4, v58
	v_lshl_add_u32 v61, v56, 4, v59
	v_add_u32_e32 v60, v182, v60
	v_add_u32_e32 v61, v182, v61
	v_add_u32_e32 v178, 0xb400, v60
	v_add_u32_e32 v179, 0x4800, v61
	v_add_u32_e32 v60, 0x9000, v60
	v_add_u32_e32 v61, 0x6c00, v61
	ds_read_b128 v[6:9], v178
	ds_read_b128 v[10:13], v178 offset:64
	ds_read_b128 v[22:25], v179
	ds_read_b128 v[26:29], v179 offset:64
	ds_read_b128 v[30:33], v179 offset:2304
	ds_read_b128 v[34:37], v179 offset:2368
	ds_read_b128 v[38:41], v179 offset:4608
	ds_read_b128 v[42:45], v179 offset:4672
	ds_read_b128 v[46:49], v179 offset:6912
	ds_read_b128 v[50:53], v179 offset:6976
	ds_read_b128 v[14:17], v60
	ds_read_b128 v[18:21], v60 offset:64
	v_lshl_add_u32 v62, v57, 2, v185
	v_lshl_add_u32 v63, v56, 3, v58
	v_add_u32_e32 v63, v182, v63
	ds_read_b32 v176, v62
	ds_read_b32 v177, v185 offset:252
	s_lshl_b32 s0, s22, 9
	s_lshl_b32 s1, s23, 7
	s_add_i32 s1, s1, s0
	s_or_b32 s0, s1, s21
	s_ashr_i32 s1, s0, 31
	s_lshl_b64 s[0:1], s[0:1], 13
	s_add_u32 s4, s89, s0
	s_addc_u32 s5, s78, s1
	s_add_u32 s6, s79, s0
	s_addc_u32 s7, s80, s1
	v_readlane_b32 s98, v253, 3
	v_readlane_b32 s99, v253, 4
	s_add_u32 s98, s98, s0
	s_addc_u32 s99, s99, s1
	s_add_u32 s98, s98, 0xff000000
	s_addc_u32 s99, s99, -1
	s_add_u32 s100, s74, s0
	s_addc_u32 s101, s75, s1
	v_readfirstlane_b32 s32, v54
	v_lshlrev_b32_e32 v64, 11, v54
	v_lshlrev_b32_e32 v65, 5, v232
	v_lshl_add_u32 v64, v232, 4, v64
	v_lshlrev_b32_e32 v66, 9, v54
	v_lshl_add_u32 v66, v232, 3, v66
	v_add_u32_e32 v67, 0x1000, v66
	v_lshlrev_b32_e32 v71, 7, v57
	v_lshl_add_u32 v71, v56, 3, v71
	v_lshlrev_b32_e32 v70, 2, v56
	v_sub_u32_e32 v70, v55, v70
	s_waitcnt lgkmcnt(4)
	v_mfma_f32_16x16x32_bf16 v[134:137], v[22:25], v[6:9], 0
	v_mfma_f32_16x16x32_bf16 v[138:141], v[30:33], v[6:9], 0
	v_mfma_f32_16x16x32_bf16 v[142:145], v[38:41], v[6:9], 0
	v_mfma_f32_16x16x32_bf16 v[146:149], v[46:49], v[6:9], 0
	v_mfma_f32_16x16x32_bf16 v[134:137], v[26:29], v[10:13], v[134:137]
	v_mfma_f32_16x16x32_bf16 v[138:141], v[34:37], v[10:13], v[138:141]
	v_mfma_f32_16x16x32_bf16 v[142:145], v[42:45], v[10:13], v[142:145]
	v_mfma_f32_16x16x32_bf16 v[146:149], v[50:53], v[10:13], v[146:149]
	ds_read_b64 v[150:151], v63
	ds_read_b64 v[152:153], v63 offset:32
	ds_read_b64 v[172:173], v63 offset:64
	ds_read_b64 v[174:175], v63 offset:96
	ds_read_b128 v[186:189], v61
	ds_read_b128 v[190:193], v61 offset:64
	ds_read_b128 v[194:197], v61 offset:2304
	ds_read_b128 v[198:201], v61 offset:2368
	ds_read_b128 v[202:205], v61 offset:4608
	ds_read_b128 v[206:209], v61 offset:4672
	ds_read_b128 v[210:213], v61 offset:6912
	s_waitcnt lgkmcnt(13)
	v_mfma_f32_16x16x32_bf16 v[236:239], v[22:25], v[14:17], 0
	v_mfma_f32_16x16x32_bf16 v[240:243], v[30:33], v[14:17], 0
	v_mfma_f32_16x16x32_bf16 v[244:247], v[38:41], v[14:17], 0
	v_mfma_f32_16x16x32_bf16 v[248:251], v[46:49], v[14:17], 0
	v_mfma_f32_16x16x32_bf16 v[236:239], v[26:29], v[18:21], v[236:239]
	v_mfma_f32_16x16x32_bf16 v[240:243], v[34:37], v[18:21], v[240:243]
	v_mfma_f32_16x16x32_bf16 v[244:247], v[42:45], v[18:21], v[244:247]
	v_mfma_f32_16x16x32_bf16 v[248:251], v[50:53], v[18:21], v[248:251]
	ds_read_b128 v[214:217], v61 offset:6976
	s_waitcnt lgkmcnt(8)
	v_mul_f32_e32 v176, 0x3fb8aa3b, v176
	v_mul_f32_e32 v177, 0x3fb8aa3b, v177
	v_exp_f32_e32 v176, v176
	v_exp_f32_e32 v177, v177
	v_cmp_eq_u32_e32 vcc, 0, v70
	v_cmp_eq_u32_e64 s[0:1], 1, v70
	v_lshlrev_b32_e32 v76, 16, v150
	v_and_b32_e32 v77, 0xffff0000, v150
	v_cndmask_b32_e32 v72, 0, v177, vcc
	v_cndmask_b32_e64 v73, 0, v177, s[0:1]
	v_cmp_eq_u32_e32 vcc, 2, v70
	v_cmp_eq_u32_e64 s[0:1], 3, v70
	v_lshlrev_b32_e32 v78, 16, v151
	v_and_b32_e32 v79, 0xffff0000, v151
	v_cndmask_b32_e32 v74, 0, v177, vcc
	v_cndmask_b32_e64 v75, 0, v177, s[0:1]
	s_waitcnt lgkmcnt(0)
	v_mfma_f32_16x16x32_bf16 v[84:87], v[6:9], v[186:189], 0
	v_mfma_f32_16x16x32_bf16 v[88:91], v[6:9], v[194:197], 0
	v_mfma_f32_16x16x32_bf16 v[92:95], v[6:9], v[202:205], 0
	v_mfma_f32_16x16x32_bf16 v[96:99], v[6:9], v[210:213], 0
	v_mfma_f32_16x16x32_bf16 v[114:117], v[14:17], v[186:189], 0
	v_mfma_f32_16x16x32_bf16 v[118:121], v[14:17], v[194:197], 0
	v_mfma_f32_16x16x32_bf16 v[122:125], v[14:17], v[202:205], 0
	v_mfma_f32_16x16x32_bf16 v[126:129], v[14:17], v[210:213], 0
	v_mfma_f32_16x16x32_bf16 v[84:87], v[10:13], v[190:193], v[84:87]
	v_mfma_f32_16x16x32_bf16 v[88:91], v[10:13], v[198:201], v[88:91]
	v_mfma_f32_16x16x32_bf16 v[92:95], v[10:13], v[206:209], v[92:95]
	v_mfma_f32_16x16x32_bf16 v[96:99], v[10:13], v[214:217], v[96:99]
	v_mfma_f32_16x16x32_bf16 v[114:117], v[18:21], v[190:193], v[114:117]
	v_mfma_f32_16x16x32_bf16 v[118:121], v[18:21], v[198:201], v[118:121]
	v_mfma_f32_16x16x32_bf16 v[122:125], v[18:21], v[206:209], v[122:125]
	v_mfma_f32_16x16x32_bf16 v[126:129], v[18:21], v[214:217], v[126:129]
	v_fma_f32 v76, v176, v76, -v134
	v_fma_f32 v77, v176, v77, -v135
	v_fma_f32 v78, v176, v78, -v136
	v_fma_f32 v79, v176, v79, -v137
	v_cvt_pk_bf16_f32 v218, v76, v77
	v_cvt_pk_bf16_f32 v219, v78, v79
	global_store_dwordx2 v71, v[218:219], s[4:5]
	v_lshlrev_b32_e32 v76, 16, v152
	v_and_b32_e32 v77, 0xffff0000, v152
	v_lshlrev_b32_e32 v78, 16, v153
	v_and_b32_e32 v79, 0xffff0000, v153
	v_fma_f32 v76, v176, v76, -v138
	v_fma_f32 v77, v176, v77, -v139
	v_fma_f32 v78, v176, v78, -v140
	v_fma_f32 v79, v176, v79, -v141
	v_cvt_pk_bf16_f32 v220, v76, v77
	v_cvt_pk_bf16_f32 v221, v78, v79
; __device__ __forceinline__ bf16_t f2bf(float f) { return (bf16_t)(pk2(f, 0.f) & 0xffffu); }
; #define LBAR() do { asm volatile("s_waitcnt lgkmcnt(0)" ::: "memory"); __builtin_amdgcn_s_barrier(); asm volatile("" ::: "memory"); } while (0)
; __device__ __forceinline__ void gdn_unit(const Ctx& X, LAS unsigned char* hl, int b, int c, int h, int tid_h, int w4, int lane, int layer) {
;     ...
;         bf16_t* mm = WSP(bf16_t, WS_MM) + (size_t)(uid - 2048) * 4096;
; #pragma unroll
;         for (int ct = 0; ct < 4; ++ct)
; #pragma unroll
;             for (int j = 0; j < 4; ++j) { const int ii = 16 * w4 + 4 * q + j, col = 16 * ct + r;
;                 mm[((w4 * 2 + (ct >> 1)) * 64 + (r >> 2) * 16 + 4 * q + j) * 8 + (ct & 1) * 4 + (r & 3)] = f2bf((ii == col ? eG63 : 0.f) - acc[ct][j]); }
; #pragma unroll
;         for (int ct = 0; ct < 4; ++ct) acc[ct] = mma16(KDT, 16 * w4, UT, 16 * ct, (f32x4){0.f, 0.f, 0.f, 0.f}, r, q);
;         store_bc(WSP(bf16_t, WS_BCS), uid, w4, r, q, acc);
;     }
;     LBAR();
	global_store_dwordx2 v71, v[220:221], s[4:5] offset:32
	v_lshlrev_b32_e32 v76, 16, v172
	v_and_b32_e32 v77, 0xffff0000, v172
	v_lshlrev_b32_e32 v78, 16, v173
	v_and_b32_e32 v79, 0xffff0000, v173
	v_fma_f32 v76, v176, v76, -v142
	v_fma_f32 v77, v176, v77, -v143
	v_fma_f32 v78, v176, v78, -v144
	v_fma_f32 v79, v176, v79, -v145
	v_cvt_pk_bf16_f32 v222, v76, v77
	v_cvt_pk_bf16_f32 v223, v78, v79
	global_store_dwordx2 v71, v[222:223], s[4:5] offset:64
	v_lshlrev_b32_e32 v76, 16, v174
	v_and_b32_e32 v77, 0xffff0000, v174
	v_lshlrev_b32_e32 v78, 16, v175
	v_and_b32_e32 v79, 0xffff0000, v175
	v_fma_f32 v76, v176, v76, -v146
	v_fma_f32 v77, v176, v77, -v147
	v_fma_f32 v78, v176, v78, -v148
	v_fma_f32 v79, v176, v79, -v149
	v_cvt_pk_bf16_f32 v226, v76, v77
	v_cvt_pk_bf16_f32 v227, v78, v79
	global_store_dwordx2 v71, v[226:227], s[4:5] offset:96
	s_cmp_eq_u32 s32, 0
	s_cselect_b32 s0, 1.0, 0
	v_fma_f32 v76, v72, s0, -v236
	v_fma_f32 v77, v73, s0, -v237
	v_fma_f32 v78, v74, s0, -v238
	v_fma_f32 v79, v75, s0, -v239
	v_cvt_pk_bf16_f32 v100, v76, v77
	v_cvt_pk_bf16_f32 v101, v78, v79
	s_cmp_eq_u32 s32, 1
	s_cselect_b32 s0, 1.0, 0
	v_fma_f32 v76, v72, s0, -v240
	v_fma_f32 v77, v73, s0, -v241
	v_fma_f32 v78, v74, s0, -v242
	v_fma_f32 v79, v75, s0, -v243
	v_cvt_pk_bf16_f32 v102, v76, v77
	v_cvt_pk_bf16_f32 v103, v78, v79
	global_store_dwordx4 v64, v[100:103], s[98:99]
	s_cmp_eq_u32 s32, 2
	s_cselect_b32 s0, 1.0, 0
	v_fma_f32 v76, v72, s0, -v244
	v_fma_f32 v77, v73, s0, -v245
	v_fma_f32 v78, v74, s0, -v246
	v_fma_f32 v79, v75, s0, -v247
	v_cvt_pk_bf16_f32 v104, v76, v77
	v_cvt_pk_bf16_f32 v105, v78, v79
	s_cmp_eq_u32 s32, 3
	s_cselect_b32 s0, 1.0, 0
	v_fma_f32 v76, v72, s0, -v248
	v_fma_f32 v77, v73, s0, -v249
	v_fma_f32 v78, v74, s0, -v250
	v_fma_f32 v79, v75, s0, -v251
	v_cvt_pk_bf16_f32 v106, v76, v77
	v_cvt_pk_bf16_f32 v107, v78, v79
	global_store_dwordx4 v64, v[104:107], s[98:99] offset:1024
	v_cvt_pk_bf16_f32 v108, v84, v85
	v_cvt_pk_bf16_f32 v109, v86, v87
	v_cvt_pk_bf16_f32 v110, v88, v89
	v_cvt_pk_bf16_f32 v111, v90, v91
	global_store_dwordx4 v65, v[108:111], s[6:7] nt
	v_cvt_pk_bf16_f32 v80, v92, v93
	v_cvt_pk_bf16_f32 v81, v94, v95
	v_cvt_pk_bf16_f32 v82, v96, v97
	v_cvt_pk_bf16_f32 v83, v98, v99
	global_store_dwordx4 v65, v[80:83], s[6:7] offset:16 nt
	v_cvt_pk_bf16_f32 v40, v114, v115
	v_cvt_pk_bf16_f32 v41, v116, v117
	global_store_dwordx2 v66, v[40:41], s[100:101]
	v_cvt_pk_bf16_f32 v42, v118, v119
	v_cvt_pk_bf16_f32 v43, v120, v121
	global_store_dwordx2 v66, v[42:43], s[100:101] offset:2048
	v_cvt_pk_bf16_f32 v44, v122, v123
	v_cvt_pk_bf16_f32 v45, v124, v125
	global_store_dwordx2 v67, v[44:45], s[100:101]
	v_cvt_pk_bf16_f32 v46, v126, v127
	v_cvt_pk_bf16_f32 v47, v128, v129
	global_store_dwordx2 v67, v[46:47], s[100:101] offset:2048
	s_branch .Lgdn_p4_pad_end
	s_nop 0
	s_nop 0
	s_nop 0
	s_nop 0
	s_nop 0
	s_nop 0
	s_nop 0
	s_nop 0
	s_nop 0
	s_nop 0
	s_nop 0
	s_nop 0
	s_nop 0
	s_nop 0
	s_nop 0
	s_nop 0
	s_nop 0
	s_nop 0
	s_nop 0
	s_nop 0
	s_nop 0
	s_nop 0
	s_nop 0
	s_nop 0
	s_nop 0
	s_nop 0
	s_nop 0
	s_nop 0
	s_nop 0
	s_nop 0
	s_nop 0
	s_nop 0
	s_nop 0
	s_nop 0
	s_nop 0
	s_nop 0
	s_nop 0
	s_nop 0
	s_nop 0
	s_nop 0
	s_nop 0
	s_nop 0
	s_nop 0
	s_nop 0
	s_nop 0
	s_nop 0
	s_nop 0
	s_nop 0
	s_nop 0
	s_nop 0
	s_nop 0
	s_nop 0
	s_nop 0
	s_nop 0
	s_nop 0
	s_nop 0
	s_nop 0
	s_nop 0
	s_nop 0
	s_nop 0
	s_nop 0
	s_nop 0
	s_nop 0
	s_nop 0
	s_nop 0
	s_nop 0
	s_nop 0
	s_nop 0
	s_nop 0
	s_nop 0
	s_nop 0
	s_nop 0
	s_nop 0
	s_nop 0
	s_nop 0
	s_nop 0
	s_nop 0
	s_nop 0
	s_nop 0
	s_nop 0
	s_nop 0
	s_nop 0
	s_nop 0
	s_nop 0
	s_nop 0
	s_nop 0
	s_nop 0
	s_nop 0
	s_nop 0
	s_nop 0
	s_nop 0
	s_nop 0
	s_nop 0
	s_nop 0
	s_nop 0
	s_nop 0
	s_nop 0
	s_nop 0
	s_nop 0
	s_nop 0
	s_nop 0
	s_nop 0
	s_nop 0
	s_nop 0
	s_nop 0
	s_nop 0
	s_nop 0
	s_nop 0
	s_nop 0
	s_nop 0
	s_nop 0
	s_nop 0
	s_nop 0
	s_nop 0
	s_nop 0
	s_nop 0
	s_nop 0
	s_nop 0
	s_nop 0
	s_nop 0
	s_nop 0
	s_nop 0
	s_nop 0
	s_nop 0
	s_nop 0
	s_nop 0
	s_nop 0
	s_nop 0
	s_nop 0
	s_nop 0
	s_nop 0
	s_nop 0
	s_nop 0
	s_nop 0
	s_nop 0
	s_nop 0
	s_nop 0
	s_nop 0
	s_nop 0
	s_nop 0
	s_nop 0
	s_nop 0
	s_nop 0
	s_nop 0
	s_nop 0
	s_nop 0
	s_nop 0
	s_nop 0
	s_nop 0
	s_nop 0
	s_nop 0
	s_nop 0
	s_nop 0
	s_nop 0
	s_nop 0
	s_nop 0
	s_nop 0
	s_nop 0
	s_nop 0
	s_nop 0
	s_nop 0
	s_nop 0
	s_nop 0
	s_nop 0
	s_nop 0
	s_nop 0
	s_nop 0
	s_nop 0
	s_nop 0
	s_nop 0
	s_nop 0
	s_nop 0
	s_nop 0
	s_nop 0
	s_nop 0
	s_nop 0
	s_nop 0
	s_nop 0
	s_nop 0
	s_nop 0
	s_nop 0
	s_nop 0
	s_nop 0
	s_nop 0
	s_nop 0
	s_nop 0
	s_nop 0
	s_nop 0
	s_nop 0
	s_nop 0
	s_nop 0
	s_nop 0
	s_nop 0
	s_nop 0
	s_nop 0
	s_nop 0
	s_nop 0
	s_nop 0
	s_nop 0
	s_nop 0
	s_nop 0
	s_nop 0
	s_nop 0
	s_nop 0
	s_nop 0
	s_nop 0
	s_nop 0
	s_nop 0
	s_nop 0
	s_nop 0
	s_nop 0
	s_nop 0
	s_nop 0
	s_nop 0
	s_nop 0
	s_nop 0
	s_nop 0
	s_nop 0
	s_nop 0
	s_nop 0
	s_nop 0
	s_nop 0
	s_nop 0
	s_nop 0
	s_nop 0
	s_nop 0
	s_nop 0
	s_nop 0
	s_nop 0
	s_nop 0
	s_nop 0
	s_nop 0
	s_nop 0
	s_nop 0
	s_nop 0
	s_nop 0
	s_nop 0
	s_nop 0
	s_nop 0
	s_nop 0
	s_nop 0
	s_nop 0
	s_nop 0
	s_nop 0
	s_nop 0
	s_nop 0
	s_nop 0
	s_nop 0
	s_nop 0
	s_nop 0
	s_nop 0
	s_nop 0
	s_nop 0
	s_nop 0
	s_nop 0
	s_nop 0
	s_nop 0
	s_nop 0
	s_nop 0
	s_nop 0
	s_nop 0
	s_nop 0
	s_nop 0
	s_nop 0
	s_nop 0
	s_nop 0
	s_nop 0
	s_nop 0
	s_nop 0
	s_nop 0
	s_nop 0
	s_nop 0
	s_nop 0
	s_nop 0
	s_nop 0
	s_nop 0
	s_nop 0
	s_nop 0
	s_nop 0
	s_nop 0
	s_nop 0
	s_nop 0
	s_nop 0
	s_nop 0
	s_nop 0
	s_nop 0
	s_nop 0
	s_nop 0
	s_nop 0
	s_nop 0
	s_nop 0
	s_nop 0
	s_nop 0
	s_nop 0
	s_nop 0
	s_nop 0
	s_nop 0
	s_nop 0
	s_nop 0
	s_nop 0
	s_nop 0
	s_nop 0
	s_nop 0
	s_nop 0
	s_nop 0
	s_nop 0
	s_nop 0
	s_nop 0
	s_nop 0
	s_nop 0
	s_nop 0
	s_nop 0
	s_nop 0
	s_nop 0
	s_nop 0
	s_nop 0
	s_nop 0
	s_nop 0
	s_nop 0
	s_nop 0
	s_nop 0
	s_nop 0
	s_nop 0
	s_nop 0
	s_nop 0
	s_nop 0
	s_nop 0
	s_nop 0
	s_nop 0
	s_nop 0
	s_nop 0
	s_nop 0
	s_nop 0
	s_nop 0
	s_nop 0
	s_nop 0
	s_nop 0
	s_nop 0
	s_nop 0
	s_nop 0
	s_nop 0
	s_nop 0
	s_nop 0
	s_nop 0
	s_nop 0
	s_nop 0
	s_nop 0
	s_nop 0
	s_nop 0
	s_nop 0
	s_nop 0
	s_nop 0
	s_nop 0
	s_nop 0
	s_nop 0
	s_nop 0
	s_nop 0

; __device__ __forceinline__ bf16_t f2bf(float f) { return (bf16_t)(pk2(f, 0.f) & 0xffffu); }
; __device__ __forceinline__ float fexp(float x) { return __expf(x); }
; #define LBAR() do { asm volatile("s_waitcnt lgkmcnt(0)" ::: "memory"); __builtin_amdgcn_s_barrier(); asm volatile("" ::: "memory"); } while (0)
; __device__ __forceinline__ void ret_unit(const Ctx& X, LAS unsigned char* hl, int b, int c, int h, int tid_h, int w4, int lane) {
;     ...
; #pragma unroll
;     for (int ct = 0; ct < 4; ++ct) acc[ct] = mma16(QR, 16 * w4, KR, 16 * ct, (f32x4){0.f, 0.f, 0.f, 0.f}, r, q);
; #pragma unroll
;     for (int ct = 0; ct < 4; ++ct)
; #pragma unroll
;         for (int j = 0; j < 4; ++j) { const int ii = 16 * w4 + 4 * q + j, col = 16 * ct + r;
;             P[ii * LT + col] = f2bf(ii >= col ? acc[ct][j] * fexp(lg * (float)(ii - col)) : 0.f); }
;     LBAR();
.LpfR_done:
	v_or_b32_e32 v6, s39, v32
	v_mul_u32_u24_e32 v19, 0x90, v6
	v_add3_u32 v10, v37, v19, v20
	v_mad_u32_u24 v14, v32, s44, v29
	ds_read_b128 v[6:9], v10
	ds_read_b128 v[38:41], v10 offset:64
	ds_read_b128 v[10:13], v14
	ds_read_b128 v[14:17], v14 offset:64
	s_waitcnt lgkmcnt(1)
	v_mfma_f32_16x16x32_bf16 v[10:13], v[6:9], v[10:13], 0
	v_ashrrev_i32_e32 v18, 4, v130
	v_or_b32_e32 v31, 16, v32
	v_or_b32_e32 v28, 32, v32
	s_waitcnt lgkmcnt(0)
	v_mfma_f32_16x16x32_bf16 v[42:45], v[38:41], v[14:17], v[10:13]
	s_add_u32 s4, s79, s0
	s_addc_u32 s5, s80, s1
	s_add_u32 s0, s74, s0
	v_mov_b32_e32 v10, 0x900
	v_mad_u32_u24 v21, v32, s44, v10
	v_add_u32_e32 v14, v29, v21
	ds_read_b128 v[10:13], v14
	ds_read_b128 v[14:17], v14 offset:64
	s_waitcnt lgkmcnt(1)
	v_mfma_f32_16x16x32_bf16 v[10:13], v[6:9], v[10:13], 0
	s_addc_u32 s1, s75, s1
	s_waitcnt lgkmcnt(0)
	v_mfma_f32_16x16x32_bf16 v[14:17], v[38:41], v[14:17], v[10:13]
	s_nop 4
	v_mov_b32_e32 v10, 0x1200
	v_mad_u32_u24 v22, v32, s44, v10
	v_add_u32_e32 v23, v29, v22
	ds_read_b128 v[10:13], v23
	ds_read_b128 v[24:27], v23 offset:64
	s_waitcnt lgkmcnt(1)
	v_mfma_f32_16x16x32_bf16 v[10:13], v[6:9], v[10:13], 0
	v_mov_b32_e32 v23, 0x1b00
	v_mad_u32_u24 v23, v32, s44, v23
	s_waitcnt lgkmcnt(0)
	v_mfma_f32_16x16x32_bf16 v[10:13], v[38:41], v[24:27], v[10:13]
	v_lshl_add_u32 v27, v18, 2, s39
	v_sub_u32_e32 v26, v27, v32
	v_cvt_f32_i32_e32 v26, v26
	v_add_u32_e32 v25, v29, v23
	ds_read_b128 v[46:49], v25
	v_cmp_ge_i32_e32 vcc, v27, v32
	v_mul_f32_e32 v26, v36, v26
	v_mul_f32_e32 v26, 0x3fb8aa3b, v26
	v_exp_f32_e32 v26, v26
	s_waitcnt lgkmcnt(0)
	v_mfma_f32_16x16x32_bf16 v[6:9], v[6:9], v[46:49], 0
	ds_read_b128 v[46:49], v25 offset:64
	v_lshlrev_b32_e32 v25, 1, v32
	v_mul_f32_e32 v26, v26, v42
	v_cndmask_b32_e32 v26, 0, v26, vcc
	v_mul_lo_u32 v29, v27, s44
	v_cvt_pk_bf16_f32 v26, v26, v157
	v_add3_u32 v25, v35, v25, v29
	v_or_b32_e32 v30, 1, v27
	ds_write_b16 v25, v26
	v_sub_u32_e32 v26, v30, v32
	v_cvt_f32_i32_e32 v26, v26
	v_cmp_ge_i32_e32 vcc, v30, v32
	v_or_b32_e32 v29, 2, v27
	v_or_b32_e32 v24, 48, v32
	v_mul_f32_e32 v26, v36, v26
	v_mul_f32_e32 v26, 0x3fb8aa3b, v26
	v_exp_f32_e32 v26, v26
	s_waitcnt lgkmcnt(1)
	v_mfma_f32_16x16x32_bf16 v[6:9], v[38:41], v[46:49], v[6:9]
	v_add_u32_e32 v38, v34, v20
	v_mad_u32_u24 v39, v32, s44, v38
	v_mul_f32_e32 v26, v26, v43
	v_cndmask_b32_e32 v26, 0, v26, vcc
	v_cvt_pk_bf16_f32 v26, v26, v157
	ds_write_b16 v25, v26 offset:144
	v_sub_u32_e32 v26, v29, v32
	v_cvt_f32_i32_e32 v26, v26
	v_cmp_ge_i32_e32 vcc, v29, v32
	v_add_u32_e32 v40, v38, v21
	v_add_u32_e32 v41, v38, v22
	v_mul_f32_e32 v26, v36, v26
	v_mul_f32_e32 v26, 0x3fb8aa3b, v26
	v_exp_f32_e32 v26, v26
	v_add_u32_e32 v38, v38, v23
	v_mul_f32_e32 v26, v26, v44
	v_cndmask_b32_e32 v26, 0, v26, vcc
	v_cvt_pk_bf16_f32 v26, v26, v157
	ds_write_b16 v25, v26 offset:288
	v_or_b32_e32 v26, 3, v27
	v_sub_u32_e32 v37, v26, v32
	v_cvt_f32_i32_e32 v37, v37
	v_cmp_ge_i32_e32 vcc, v26, v32
	v_mul_f32_e32 v37, v36, v37
	v_mul_f32_e32 v37, 0x3fb8aa3b, v37
	v_exp_f32_e32 v37, v37
	s_nop 0
	v_mul_f32_e32 v37, v37, v45
	v_cndmask_b32_e32 v37, 0, v37, vcc
	v_cvt_pk_bf16_f32 v37, v37, v157
	ds_write_b16 v25, v37 offset:432
	v_sub_u32_e32 v37, v27, v31
	v_cvt_f32_i32_e32 v37, v37
	v_cmp_ge_i32_e32 vcc, v27, v31
	v_mul_f32_e32 v37, v36, v37
	v_mul_f32_e32 v37, 0x3fb8aa3b, v37
	v_exp_f32_e32 v37, v37
	s_nop 0
	v_mul_f32_e32 v14, v37, v14
	v_cndmask_b32_e32 v14, 0, v14, vcc
	v_cvt_pk_bf16_f32 v14, v14, v157
	ds_write_b16 v25, v14 offset:32
	v_sub_u32_e32 v14, v30, v31
	v_cvt_f32_i32_e32 v14, v14
	v_cmp_ge_i32_e32 vcc, v30, v31
	v_mul_f32_e32 v14, v36, v14
	v_mul_f32_e32 v14, 0x3fb8aa3b, v14
	v_exp_f32_e32 v14, v14
	s_nop 0
	v_mul_f32_e32 v14, v14, v15
	v_cndmask_b32_e32 v14, 0, v14, vcc
	v_cvt_pk_bf16_f32 v14, v14, v157
	ds_write_b16 v25, v14 offset:176
	v_sub_u32_e32 v14, v29, v31
	v_cvt_f32_i32_e32 v14, v14
	v_cmp_ge_i32_e32 vcc, v29, v31
	v_mul_f32_e32 v14, v36, v14
	v_mul_f32_e32 v14, 0x3fb8aa3b, v14
	v_exp_f32_e32 v14, v14
	s_nop 0
	v_mul_f32_e32 v14, v14, v16
	v_cndmask_b32_e32 v14, 0, v14, vcc
	v_cvt_pk_bf16_f32 v14, v14, v157
	ds_write_b16 v25, v14 offset:320
	v_sub_u32_e32 v14, v26, v31
	v_cvt_f32_i32_e32 v14, v14
	v_cmp_ge_i32_e32 vcc, v26, v31
	v_mul_f32_e32 v14, v36, v14
	v_mul_f32_e32 v14, 0x3fb8aa3b, v14
	v_exp_f32_e32 v14, v14
	s_nop 0
	v_mul_f32_e32 v14, v14, v17
	v_cndmask_b32_e32 v14, 0, v14, vcc
	v_cvt_pk_bf16_f32 v14, v14, v157
	ds_write_b16 v25, v14 offset:464
	v_sub_u32_e32 v14, v27, v28
	v_cvt_f32_i32_e32 v14, v14
	v_cmp_ge_i32_e32 vcc, v27, v28
	v_mul_f32_e32 v14, v36, v14
	v_mul_f32_e32 v14, 0x3fb8aa3b, v14
	v_exp_f32_e32 v14, v14
	s_nop 0
	v_mul_f32_e32 v10, v14, v10
	v_cndmask_b32_e32 v10, 0, v10, vcc
	v_cvt_pk_bf16_f32 v10, v10, v157
	ds_write_b16 v25, v10 offset:64
	v_sub_u32_e32 v10, v30, v28
	v_cvt_f32_i32_e32 v10, v10
	v_cmp_ge_i32_e32 vcc, v30, v28
	v_mul_f32_e32 v10, v36, v10
	v_mul_f32_e32 v10, 0x3fb8aa3b, v10
	v_exp_f32_e32 v10, v10
	s_nop 0
	v_mul_f32_e32 v10, v10, v11
	v_cndmask_b32_e32 v10, 0, v10, vcc
	v_cvt_pk_bf16_f32 v10, v10, v157
	ds_write_b16 v25, v10 offset:208
	v_sub_u32_e32 v10, v29, v28
	v_cvt_f32_i32_e32 v10, v10
	v_cmp_ge_i32_e32 vcc, v29, v28
	v_mul_f32_e32 v10, v36, v10
	v_mul_f32_e32 v10, 0x3fb8aa3b, v10
	v_exp_f32_e32 v10, v10
	s_nop 0
	v_mul_f32_e32 v10, v10, v12
	v_cndmask_b32_e32 v10, 0, v10, vcc
	v_cvt_pk_bf16_f32 v10, v10, v157
	ds_write_b16 v25, v10 offset:352
	v_sub_u32_e32 v10, v26, v28
	v_cvt_f32_i32_e32 v10, v10
	v_cmp_ge_i32_e32 vcc, v26, v28
	v_mul_f32_e32 v10, v36, v10
	v_mul_f32_e32 v10, 0x3fb8aa3b, v10
	v_exp_f32_e32 v10, v10
	s_nop 0
	v_mul_f32_e32 v10, v10, v13
	v_cndmask_b32_e32 v10, 0, v10, vcc
	v_cvt_pk_bf16_f32 v10, v10, v157
	ds_write_b16 v25, v10 offset:496
	v_sub_u32_e32 v10, v27, v24
	v_cvt_f32_i32_e32 v10, v10
	v_cmp_ge_i32_e32 vcc, v27, v24
	v_mul_f32_e32 v10, v36, v10
	v_mul_f32_e32 v10, 0x3fb8aa3b, v10
	v_exp_f32_e32 v10, v10
	s_nop 0
	v_mul_f32_e32 v6, v10, v6
	v_cndmask_b32_e32 v6, 0, v6, vcc
	v_cvt_pk_bf16_f32 v6, v6, v157
	ds_write_b16 v25, v6 offset:96
	v_sub_u32_e32 v6, v30, v24
	v_cvt_f32_i32_e32 v6, v6
	v_cmp_ge_i32_e32 vcc, v30, v24
	v_add3_u32 v10, v35, v19, v20
	v_mul_f32_e32 v6, v36, v6
	v_mul_f32_e32 v6, 0x3fb8aa3b, v6
	v_exp_f32_e32 v6, v6
	s_nop 0
	v_mul_f32_e32 v6, v6, v7
	v_cndmask_b32_e32 v6, 0, v6, vcc
	v_cvt_pk_bf16_f32 v6, v6, v157
	ds_write_b16 v25, v6 offset:240
	v_sub_u32_e32 v6, v29, v24
	v_cvt_f32_i32_e32 v6, v6
	v_cmp_ge_i32_e32 vcc, v29, v24
	v_mul_f32_e32 v6, v36, v6
	v_mul_f32_e32 v6, 0x3fb8aa3b, v6
	v_exp_f32_e32 v6, v6
	s_nop 0
	v_mul_f32_e32 v6, v6, v8
	v_cndmask_b32_e32 v6, 0, v6, vcc
	v_cvt_pk_bf16_f32 v6, v6, v157
	ds_write_b16 v25, v6 offset:384
	v_sub_u32_e32 v6, v26, v24
	v_cvt_f32_i32_e32 v6, v6
	v_cmp_ge_i32_e32 vcc, v26, v24
	v_mul_f32_e32 v6, v36, v6
	v_mul_f32_e32 v6, 0x3fb8aa3b, v6
	v_exp_f32_e32 v6, v6
	s_nop 0
	v_mul_f32_e32 v6, v6, v9
	v_cndmask_b32_e32 v6, 0, v6, vcc
	v_cvt_pk_bf16_f32 v6, v6, v157
	ds_write_b16 v25, v6 offset:528
	s_waitcnt lgkmcnt(0)
	s_barrier
; #define LBAR() do { asm volatile("s_waitcnt lgkmcnt(0)" ::: "memory"); __builtin_amdgcn_s_barrier(); asm volatile("" ::: "memory"); } while (0)
; __device__ __forceinline__ void ret_unit(const Ctx& X, LAS unsigned char* hl, int b, int c, int h, int tid_h, int w4, int lane) {
;     ...
; #pragma unroll
;     for (int ct = 0; ct < 4; ++ct) acc[ct] = mma16(P, 16 * w4, VT, 16 * ct, (f32x4){0.f, 0.f, 0.f, 0.f}, r, q);
;     store_oloc(WSP(bf16_t, WS_OLOC), uid, w4, lane, acc);
; #pragma unroll
;     for (int ct = 0; ct < 4; ++ct) acc[ct] = mma16(KDT, 16 * w4, VT, 16 * ct, (f32x4){0.f, 0.f, 0.f, 0.f}, r, q);
;     store_bc(WSP(bf16_t, WS_BCS), uid, w4, r, q, acc);
;     LBAR();
	v_add3_u32 v42, v33, v19, v20
	ds_read_b128 v[46:49], v10
	ds_read_b128 v[50:53], v10 offset:64
	ds_read_b128 v[54:57], v39
	ds_read_b128 v[58:61], v39 offset:64
	ds_read_b128 v[62:65], v40
	ds_read_b128 v[66:69], v40 offset:64
	ds_read_b128 v[72:75], v41
	ds_read_b128 v[76:79], v41 offset:64
	ds_read_b128 v[80:83], v38
	ds_read_b128 v[102:105], v38 offset:64
	ds_read_b128 v[134:137], v42
	ds_read_b128 v[138:141], v42 offset:64
	v_lshlrev_b32_e32 v6, 4, v130
	v_ashrrev_i32_e32 v7, 31, v6
	v_lshl_add_u64 v[22:23], v[6:7], 1, s[4:5]
	v_lshl_or_b32 v12, v32, 2, s81
	v_lshl_add_u32 v12, v18, 6, v12
	v_ashrrev_i32_e32 v13, 31, v12
	v_lshl_add_u64 v[14:15], v[12:13], 1, s[0:1]
	v_add_u32_e32 v16, 0x800, v12
	v_ashrrev_i32_e32 v17, 31, v16
	v_lshl_add_u64 v[16:17], v[16:17], 1, s[0:1]
	v_add_u32_e32 v8, 0xc00, v12
	v_ashrrev_i32_e32 v9, 31, v8
	v_lshl_add_u64 v[8:9], v[8:9], 1, s[0:1]
	s_waitcnt lgkmcnt(2)
	v_mfma_f32_16x16x32_bf16 v[186:189], v[46:49], v[54:57], 0
	v_mfma_f32_16x16x32_bf16 v[190:193], v[46:49], v[62:65], 0
	v_mfma_f32_16x16x32_bf16 v[194:197], v[46:49], v[72:75], 0
	v_mfma_f32_16x16x32_bf16 v[198:201], v[46:49], v[80:83], 0
	v_mfma_f32_16x16x32_bf16 v[186:189], v[50:53], v[58:61], v[186:189]
	v_mfma_f32_16x16x32_bf16 v[190:193], v[50:53], v[66:69], v[190:193]
	v_mfma_f32_16x16x32_bf16 v[194:197], v[50:53], v[76:79], v[194:197]
	v_mfma_f32_16x16x32_bf16 v[198:201], v[50:53], v[102:105], v[198:201]
	s_waitcnt lgkmcnt(0)
	v_mfma_f32_16x16x32_bf16 v[202:205], v[134:137], v[54:57], 0
	v_mfma_f32_16x16x32_bf16 v[206:209], v[134:137], v[62:65], 0
	v_mfma_f32_16x16x32_bf16 v[210:213], v[134:137], v[72:75], 0
	v_mfma_f32_16x16x32_bf16 v[214:217], v[134:137], v[80:83], 0
	v_mfma_f32_16x16x32_bf16 v[202:205], v[138:141], v[58:61], v[202:205]
	v_mfma_f32_16x16x32_bf16 v[206:209], v[138:141], v[66:69], v[206:209]
	v_mfma_f32_16x16x32_bf16 v[210:213], v[138:141], v[76:79], v[210:213]
	v_mfma_f32_16x16x32_bf16 v[214:217], v[138:141], v[102:105], v[214:217]
	v_cvt_pk_bf16_f32 v218, v186, v187
	v_cvt_pk_bf16_f32 v219, v188, v189
	v_cvt_pk_bf16_f32 v220, v190, v191
	v_cvt_pk_bf16_f32 v221, v192, v193
	v_cvt_pk_bf16_f32 v236, v194, v195
	v_cvt_pk_bf16_f32 v237, v196, v197
	v_cvt_pk_bf16_f32 v238, v198, v199
	v_cvt_pk_bf16_f32 v239, v200, v201
	global_store_dwordx4 v[22:23], v[218:221], off nt
	global_store_dwordx4 v[22:23], v[236:239], off offset:16 nt
	v_cvt_pk_bf16_f32 v246, v202, v203
	v_cvt_pk_bf16_f32 v247, v204, v205
	v_cvt_pk_bf16_f32 v248, v206, v207
	v_cvt_pk_bf16_f32 v249, v208, v209
	v_cvt_pk_bf16_f32 v250, v210, v211
	v_cvt_pk_bf16_f32 v251, v212, v213
	v_cvt_pk_bf16_f32 v226, v214, v215
	v_cvt_pk_bf16_f32 v227, v216, v217
	global_store_dwordx2 v[14:15], v[246:247], off
	global_store_dwordx2 v[14:15], v[248:249], off offset:2048
	global_store_dwordx2 v[16:17], v[250:251], off
	global_store_dwordx2 v[8:9], v[226:227], off
	s_waitcnt lgkmcnt(0)
	s_barrier
	s_branch .LBB0_233
